# attention: one static s_setprio 1 for waves 4-7 over the attention units (reset before the HGRN part)
# speedup vs baseline: 1.0023x; 1.0023x over previous
; __device__ __forceinline__ lbraw_t lb_load(const float* lbsrc, int layer, int ch) { lbraw_t r = {0.f, 0.f}; if (layer != 0) { r.x = lbsrc[ch]; r.y = lbsrc[HW + ch]; } return r; }
; template <int PASS>
; __device__ __forceinline__ void hg_load(HgRaw& R, int unit, const bf16* proj, int tid) {
;     const int bh = unit >> 7, c = unit & 127, b = bh >> 3, h = bh & 7; const size_t row0 = (size_t)b * SEQ + (size_t)c * 64; const int k = tid & 127, tg = tid >> 7;
;     const bf16* pz = proj + (row0 + 16 * tg) * INW + h * 128 + k;
; #pragma unroll
;     for (int j = 0; j < 16; ++j) { const unsigned z = pz[(size_t)j * INW + C_FH]; const unsigned q = (PASS == 3) ? pz[(size_t)j * INW + C_QH] : 0u; R.zq[j] = z | (q << 16); }
; #pragma unroll
;     for (int j = 0; j < 8; ++j) { const unsigned a = pz[(size_t)(2 * j) * INW + C_IH], b2 = pz[(size_t)(2 * j + 1) * INW + C_IH]; R.vv[j] = a | (b2 << 16); }
; }
; __global__ void __launch_bounds__(NTHREADS, 2) hymba_fwd(Args args) {
;     ...
;             {   int tid2 = tid; asm volatile("" : "+v"(tid2));
;     ...
;                 HgRaw cur, nxt; const int u0 = vcu < 2048 ? vcu : 2047; hg_load<1>(cur, u0, BIG, tid);
;                 lbraw_t lbc = lb_load(args.in[12], layer, ((u0 >> 7) & 7) * 128 + (tid & 127)), lbn;
;                 for (int u = vcu; u < 2048; u += G) { const int un = u + G < 2048 ? u + G : u; hg_load<1>(nxt, un, BIG, tid); lbn = lb_load(args.in[12], layer, ((un >> 7) & 7) * 128 + (tid & 127));
.LBB0_74:
	s_setprio 0
	s_waitcnt vmcnt(0)
	v_mov_b32_e32 v16, v246
	v_readlane_b32 s4, v252, 27
	v_ashrrev_i32_e32 v0, 3, v16
	v_and_b32_e32 v18, -16, v0
	v_ashrrev_i32_e32 v19, 31, v18
	v_readlane_b32 s5, v252, 28
	s_waitcnt lgkmcnt(0)
	v_and_b32_e32 v21, 0x7f, v16
	v_lshlrev_b32_e32 v220, 1, v21
	v_lshl_add_u64 v[0:1], s[4:5], 0, v[18:19]
	v_readlane_b32 s4, v252, 30
	v_readlane_b32 s5, v252, 31
	s_movk_i32 s64, 0x2000
	s_movk_i32 s65, 0x5000
	s_waitcnt lgkmcnt(1)
	v_mov_b64_e32 v[2:3], s[4:5]
	v_mad_u64_u32 v[2:3], s[4:5], v0, s99, v[2:3]
	v_mov_b32_e32 v0, v3
	v_mad_u64_u32 v[0:1], s[4:5], v1, s99, v[0:1]
	v_mov_b32_e32 v3, v0
	v_lshl_add_u64 v[0:1], v[2:3], 0, v[220:221]
	v_add_co_u32_e32 v2, vcc, s64, v0
	s_mov_b32 s2, 0x13000
	s_nop 0
	v_addc_co_u32_e32 v3, vcc, 0, v1, vcc
	s_waitcnt lgkmcnt(0)
	v_add_co_u32_e32 v4, vcc, s65, v0
	global_load_ushort v56, v[2:3], off
	s_nop 0
	v_addc_co_u32_e32 v5, vcc, 0, v1, vcc
	global_load_ushort v57, v[4:5], off offset:2048
	v_add_co_u32_e32 v4, vcc, s47, v0
	v_readlane_b32 s62, v255, 15
	s_nop 0
	v_addc_co_u32_e32 v5, vcc, 0, v1, vcc
	v_add_co_u32_e32 v6, vcc, s46, v0
	global_load_ushort v55, v[4:5], off
	s_nop 0
	v_addc_co_u32_e32 v7, vcc, 0, v1, vcc
	global_load_ushort v54, v[6:7], off offset:2048
	v_add_co_u32_e32 v6, vcc, s15, v0
	s_add_i32 s4, s62, 12
	s_nop 0
	v_addc_co_u32_e32 v7, vcc, 0, v1, vcc
	v_add_co_u32_e32 v8, vcc, s2, v0
	s_mov_b32 s2, 0x17000
	s_nop 0
	v_addc_co_u32_e32 v9, vcc, 0, v1, vcc
	global_load_ushort v53, v[8:9], off offset:2048
	v_add_co_u32_e32 v8, vcc, s2, v0
	s_mov_b32 s2, 0x1a000
	s_nop 0
	v_addc_co_u32_e32 v9, vcc, 0, v1, vcc
	v_add_co_u32_e32 v10, vcc, s2, v0
	s_mov_b32 s2, 0x1e000
	s_nop 0
	v_addc_co_u32_e32 v11, vcc, 0, v1, vcc
	v_add_co_u32_e32 v22, vcc, s2, v0
	s_mov_b32 s2, 0x21000
	s_nop 0
	v_addc_co_u32_e32 v23, vcc, 0, v1, vcc
	global_load_ushort v52, v[6:7], off
	global_load_ushort v51, v[8:9], off
	global_load_ushort v50, v[10:11], off offset:2048
	global_load_ushort v27, v[22:23], off
	v_add_co_u32_e32 v10, vcc, s2, v0
	s_mov_b32 s2, 0x25000
	s_nop 0
	v_addc_co_u32_e32 v11, vcc, 0, v1, vcc
	v_add_co_u32_e32 v24, vcc, s2, v0
	global_load_ushort v26, v[10:11], off offset:2048
	s_nop 0
	v_addc_co_u32_e32 v25, vcc, 0, v1, vcc
	global_load_ushort v14, v[24:25], off
	v_add_co_u32_e32 v10, vcc, s94, v0
	s_mov_b32 s2, 0x2c000
	s_nop 0
	v_addc_co_u32_e32 v11, vcc, 0, v1, vcc
	v_add_co_u32_e32 v28, vcc, s2, v0
	s_mov_b32 s2, 0x2f000
	s_nop 0
	v_addc_co_u32_e32 v29, vcc, 0, v1, vcc
	global_load_ushort v15, v[10:11], off offset:2048
	global_load_ushort v13, v[28:29], off
	v_add_co_u32_e32 v10, vcc, s2, v0
	s_mov_b32 s2, 0x33000
	s_nop 0
	v_addc_co_u32_e32 v11, vcc, 0, v1, vcc
	v_add_co_u32_e32 v30, vcc, s2, v0
	s_mov_b32 s2, 0x36000
	s_nop 0
	v_addc_co_u32_e32 v31, vcc, 0, v1, vcc
	v_add_co_u32_e32 v32, vcc, s2, v0
	s_movk_i32 s2, 0x6000
	s_nop 0
	v_addc_co_u32_e32 v33, vcc, 0, v1, vcc
	global_load_ushort v12, v[10:11], off offset:2048
	s_cmp_gt_u32 s4, 24
	global_load_ushort v11, v[30:31], off
	global_load_ushort v10, v[32:33], off offset:2048
	s_nop 0
	global_load_ushort v2, v[2:3], off offset:2048
	v_add_co_u32_e32 v32, vcc, s2, v0
	s_mov_b32 s2, 0xd000
	s_nop 0
	v_addc_co_u32_e32 v33, vcc, 0, v1, vcc
	global_load_ushort v3, v[32:33], off
	s_nop 0
	global_load_ushort v4, v[4:5], off offset:2048
	v_add_co_u32_e32 v32, vcc, s2, v0
	s_mov_b32 s2, 0x14000
	s_nop 0
	v_addc_co_u32_e32 v33, vcc, 0, v1, vcc
	global_load_ushort v5, v[32:33], off
	s_nop 0
	global_load_ushort v6, v[6:7], off offset:2048
	v_add_co_u32_e32 v32, vcc, s2, v0
	s_mov_b32 s2, 0x1b000
	s_nop 0
	v_addc_co_u32_e32 v33, vcc, 0, v1, vcc
	global_load_ushort v7, v[32:33], off
	s_nop 0
	global_load_ushort v8, v[8:9], off offset:2048
	v_add_co_u32_e32 v32, vcc, s2, v0
	s_mov_b32 s2, 0x22000
	s_nop 0
	v_addc_co_u32_e32 v33, vcc, 0, v1, vcc
	global_load_ushort v9, v[32:33], off
	global_load_ushort v17, v[22:23], off offset:2048
	v_add_co_u32_e32 v22, vcc, s2, v0
	s_mov_b32 s2, 0x29000
	s_nop 0
	v_addc_co_u32_e32 v23, vcc, 0, v1, vcc
	global_load_ushort v20, v[22:23], off
	s_nop 0
	global_load_ushort v22, v[24:25], off offset:2048
	v_add_co_u32_e32 v24, vcc, s2, v0
	v_mov_b32_e32 v69, 0
	s_nop 0
	v_addc_co_u32_e32 v25, vcc, 0, v1, vcc
	global_load_ushort v23, v[24:25], off
	s_nop 0
	global_load_ushort v24, v[28:29], off offset:2048
	v_add_co_u32_e32 v28, vcc, 0x30000, v0
	s_cselect_b64 s[36:37], -1, 0
	s_nop 0
	v_addc_co_u32_e32 v29, vcc, 0, v1, vcc
	v_add_co_u32_e32 v0, vcc, 0x37000, v0
	global_load_ushort v25, v[28:29], off
	s_nop 0
	global_load_ushort v28, v[30:31], off offset:2048
	v_addc_co_u32_e32 v1, vcc, 0, v1, vcc
	global_load_ushort v29, v[0:1], off
	s_cmp_lt_u32 s4, 25
	v_mov_b32_e32 v72, 0
	s_cbranch_scc1 .LBB0_76
	v_readlane_b32 s4, v252, 29
	v_readlane_b32 s16, v252, 48
	v_mov_b32_e32 v1, v221
	v_or_b32_e32 v0, s4, v21
	v_lshlrev_b32_e32 v0, 2, v0
	v_readlane_b32 s24, v252, 56
	v_readlane_b32 s25, v252, 57
	v_readlane_b32 s17, v252, 49
	v_readlane_b32 s18, v252, 50
	v_lshl_add_u64 v[30:31], s[24:25], 0, v[0:1]
	v_readlane_b32 s19, v252, 51
	v_readlane_b32 s20, v252, 52
	global_load_dword v69, v0, s[24:25]
	v_add_co_u32_e32 v0, vcc, 0x1000, v30
	v_readlane_b32 s21, v252, 53
	s_nop 0
	v_addc_co_u32_e32 v1, vcc, 0, v31, vcc
	global_load_dword v72, v[0:1], off
	v_readlane_b32 s22, v252, 54
	v_readlane_b32 s23, v252, 55
	v_readlane_b32 s26, v252, 58
	v_readlane_b32 s27, v252, 59
	v_readlane_b32 s28, v252, 60
	v_readlane_b32 s29, v252, 61
	v_readlane_b32 s30, v252, 62
	v_readlane_b32 s31, v252, 63

;   #define PIN(x) asm volatile("":"+v"(x))
; template<int THRL> __device__ __forceinline__ void attn_unit(int b,int qcol,int kcol,int vcol,int ocol,int qb,const bf16*__restrict__ P,bf16*__restrict__ O,char*shm){
;   int tid_o=threadIdx.x; asm volatile("":"+v"(tid_o)); const int tid=tid_o,lane=tid&63,r32=lane&31,hi=lane>>5; const int wid=__builtin_amdgcn_readfirstlane(tid>>6);
;   const long rowbase=(long)b*SEQ; const int q0=qb*QB;
;   const bf16*Qw=P+(rowbase+q0+wid*QBLK)*PIN+qcol;
;   const bf16*Kh=P+rowbase*PIN+kcol,*Vh=P+rowbase*PIN+vcol;
;   const unsigned lds0=(unsigned)(uintptr_t)shm;
;   float*wsf=(float*)(shm+LDS_WS)+wid*64;
;   const bf16*ksrc=Kh+(long)lane*PIN+wid*8;
;   const bf16*vsrc=Vh+(long)(16*(wid&3)+(lane>>2))*PIN+(wid>>2)*32+(lane&3)*8;
;   const unsigned kdst=lds0+LDS_K+wid*1024, vdst=lds0+LDS_V+wid*1024;
;     ...
;   const int vb0=(int)(lds0+LDS_V)+((lane>>4)&1)*32+(lane&3)*8+(4*hi+((lane&15)>>2))*64;
.LBB0_86:
	s_waitcnt vmcnt(0)
	v_mov_b32_e32 v34, v238
	s_lshl_b32 s23, s22, 8
	v_readfirstlane_b32 s17, v34
	s_ashr_i32 s16, s17, 6
	s_add_u32 s4, s8, s23
	s_addc_u32 s5, s9, 0
	s_lshl_b32 s20, s16, 5
	s_ashr_i32 s6, s20, 31
	s_add_u32 s66, s4, s20
	s_addc_u32 s67, s5, s6
	s_mul_i32 s4, s67, 0x3800
	s_mul_hi_u32 s5, s66, 0x3800
	v_and_b32_e32 v247, 63, v34
	s_add_i32 s5, s5, s4
	s_mul_i32 s4, s66, 0x3800
	s_add_u32 s4, s82, s4
	v_mul_u32_u24_e32 v0, 0x1c00, v247
	s_addc_u32 s5, s90, s5
	v_lshlrev_b32_e32 v220, 1, v0
	s_lshl_b32 s6, s16, 3
	s_waitcnt lgkmcnt(0)
	v_lshl_add_u64 v[0:1], s[10:11], 0, v[220:221]
	s_ashr_i32 s7, s6, 31
	v_lshl_add_u64 v[16:17], s[6:7], 1, v[0:1]
	s_mov_b64 s[6:7], 0x800
	v_lshl_add_u64 v[230:231], v[16:17], 0, s[6:7]
	s_lshl_b32 s6, s16, 4
	v_bfe_u32 v0, v34, 2, 4
	v_and_or_b32 v0, s6, 48, v0
	s_ashr_i32 s6, s17, 3
	s_andn2_b32 s6, s6, 31
	v_mul_u32_u24_e32 v0, 0x1c00, v0
	s_ashr_i32 s7, s6, 31
	s_lshl_b32 s21, s16, 10
	v_lshlrev_b32_e32 v220, 1, v0
	v_lshlrev_b32_e32 v249, 3, v34
	s_cmp_lg_u32 0, -1
	v_lshl_add_u64 v[0:1], s[12:13], 0, v[220:221]
	v_and_b32_e32 v251, 24, v249
	s_cselect_b32 s18, 0, 0
	v_lshl_add_u64 v[0:1], s[6:7], 1, v[0:1]
	v_lshlrev_b32_e32 v2, 1, v251
	s_waitcnt lgkmcnt(1)
	v_mov_b32_e32 v3, v221
	s_add_i32 s18, s21, s18
	s_cmp_lt_u32 s18, 0x1000
	s_cbranch_scc1 .Lattn_noprio
	s_setprio 1
; #define WAIT_BAR(N) asm volatile("s_waitcnt vmcnt(" #N ") lgkmcnt(0)\n\ts_barrier":::"memory")
;   #define DMA_K(t,slot) glds16(ksrc+(long)(t)*KVBLK*PIN,(unsigned)__builtin_amdgcn_readfirstlane(kdst+(slot)))
;   #define DMA_V(t,slot) do{ glds16(vsrc+(long)(t)*KVBLK*PIN,(unsigned)__builtin_amdgcn_readfirstlane(vdst+2*(slot))); glds16(vsrc+(long)(t)*KVBLK*PIN+64,(unsigned)__builtin_amdgcn_readfirstlane(vdst+2*(slot)+SLOTB)); }while(0)
;   #define CMASK(P0,P1,t) do{int jb_=(t)-(NT-4); if(jb_>=0)cmask(P0,P1,jb_,qrel,hi);}while(0)
;   #define PIN(x) asm volatile("":"+v"(x))
;   #define CMASK(P0,P1,t) do{}while(0)
;   #define CMASK(P0,P1,t) do{int jb_=(t)-(NT-4); if(jb_>=0)cmask(P0,P1,jb_,qrel,hi);}while(0)
; __device__ __forceinline__ void cmask(f32x16&p0,f32x16&p1,int jb,int qrel,int hi){
;   const float NEG=-INFINITY; int kb=64*jb+4*hi;
;   #pragma unroll
;   for(int r=0;r<16;++r){int kv=kb+(r&3)+8*(r>>2); if(kv>qrel)p0[r]=NEG; if(kv+32>qrel)p1[r]=NEG;}
; }
; template<int THRL> __device__ __forceinline__ void attn_unit(int b,int qcol,int kcol,int vcol,int ocol,int qb,const bf16*__restrict__ P,bf16*__restrict__ O,char*shm){
;     ...
;   DMA_K(0,0);DMA_V(0,0);DMA_K(1,SLOTB);
;   bf16x8 qr[4];
;   #pragma unroll
;   for(int d0=0;d0<4;++d0)qr[d0]=*reinterpret_cast<const bf16x8*>(&Qw[(long)r32*PIN+d0*16+hi*8]);
;   float mhat=0.f,l_reg=0.f;f32x16 o[4];o[0]=f32x16{};o[1]=f32x16{};o[2]=f32x16{};o[3]=f32x16{};f32x16 negm=f32x16{};asm volatile("":"+v"(negm));
;   const int qrel=wid*QBLK+r32;
;     ...
;   bool resc=false;
;     ...
;   f32x16 pA0,pA1,pB0,pB1;
;   int sl_prev=0,sl_cur=0,sl_next=SLOTB;
;     ...
;   DMA_K(2,2*SLOTB);
;   WAIT_BAR(4);
;   qkt(pA0,pA1,Kbase,qr,negm,r32,hi);asm volatile("s_nop 15\n\ts_nop 7":"+v"(pA0),"+v"(pA1));CMASK(pA0,pA1,0);
.Lattn_noprio:
	s_mov_b32 s24, m0
	s_mov_b32 m0, s18
	s_nop 0
	global_load_lds_dwordx4 v[230:231], off
	s_mov_b32 m0, s24
	v_lshl_add_u64 v[32:33], v[0:1], 0, v[2:3]
	s_add_i32 s19, s18, 0x6000
	s_mov_b32 s24, m0
	s_mov_b32 m0, s19
	s_nop 0
	global_load_lds_dwordx4 v[32:33], off
	s_mov_b32 m0, s24
	s_mov_b64 s[24:25], 0x80
	v_lshl_add_u64 v[0:1], v[32:33], 0, s[24:25]
	s_add_i32 s24, s18, 0x8000
	s_mov_b32 s25, m0
	s_mov_b32 m0, s24
	s_nop 0
	global_load_lds_dwordx4 v[0:1], off
	s_mov_b32 m0, s25
	s_mov_b64 s[24:25], 0xe0800
	v_and_b32_e32 v248, 31, v34
	v_lshl_add_u64 v[0:1], v[16:17], 0, s[24:25]
	s_add_i32 s24, s18, 0x2000
	s_mov_b32 s25, m0
	s_mov_b32 m0, s24
	s_nop 0
	global_load_lds_dwordx4 v[0:1], off
	s_mov_b32 m0, s25
	v_mul_u32_u24_e32 v0, 0x1c00, v248
	v_bfe_u32 v232, v34, 5, 1
	v_lshlrev_b32_e32 v0, 1, v0
	v_lshl_or_b32 v14, v232, 4, v0
	global_load_dwordx4 v[172:175], v14, s[4:5]
	global_load_dwordx4 v[168:171], v14, s[4:5] offset:32
	global_load_dwordx4 v[160:163], v14, s[4:5] offset:64
	global_load_dwordx4 v[152:155], v14, s[4:5] offset:96
	v_mov_b32_e32 v0, v221
	v_mov_b32_e32 v1, v221
	v_mov_b32_e32 v2, v221
	s_waitcnt lgkmcnt(0)
	v_mov_b32_e32 v4, v221
	v_mov_b32_e32 v5, v221
	v_mov_b32_e32 v6, v221
	v_mov_b32_e32 v7, v221
	v_mov_b32_e32 v8, v221
	v_mov_b32_e32 v9, v221
	v_mov_b32_e32 v10, v221
	v_mov_b32_e32 v11, v221
	v_mov_b32_e32 v12, v221
	v_mov_b32_e32 v13, v221
	v_mov_b32_e32 v14, v221
	v_mov_b32_e32 v15, v221
	s_mov_b64 s[4:5], 0x1c0800
	v_lshlrev_b32_e32 v18, 10, v232
	v_lshlrev_b32_e32 v19, 4, v248
	v_lshl_add_u64 v[16:17], v[16:17], 0, s[4:5]
	s_add_i32 s4, s18, 0x4000
	s_mov_b32 s5, m0
	s_mov_b32 m0, s4
	s_nop 0
	global_load_lds_dwordx4 v[16:17], off
	s_mov_b32 m0, s5
	v_add3_u32 v224, 0, v18, v19
	s_waitcnt vmcnt(4) lgkmcnt(0)
	s_barrier
	ds_read_b128 v[36:39], v224
	s_cmp_lg_u32 s22, 0
	s_cselect_b64 s[4:5], -1, 0
	v_lshlrev_b32_e32 v250, 2, v232
	v_or_b32_e32 v222, s20, v248
	s_and_b64 vcc, exec, s[4:5]
	s_waitcnt vmcnt(3) lgkmcnt(0)
	v_mfma_f32_32x32x16_bf16 v[16:31], v[36:39], v[172:175], v[0:15]
	ds_read_b128 v[36:39], v224 offset:512
	s_waitcnt lgkmcnt(0)
	v_mfma_f32_32x32x16_bf16 v[0:15], v[36:39], v[172:175], v[0:15]
	ds_read_b128 v[36:39], v224 offset:2048
	s_waitcnt vmcnt(2) lgkmcnt(0)
	v_mfma_f32_32x32x16_bf16 v[16:31], v[36:39], v[168:171], v[16:31]
	ds_read_b128 v[36:39], v224 offset:2560
	s_waitcnt lgkmcnt(0)
	v_mfma_f32_32x32x16_bf16 v[0:15], v[36:39], v[168:171], v[0:15]
	ds_read_b128 v[36:39], v224 offset:4096
	s_waitcnt vmcnt(1) lgkmcnt(0)
	v_mfma_f32_32x32x16_bf16 v[16:31], v[36:39], v[160:163], v[16:31]
	ds_read_b128 v[36:39], v224 offset:4608
	s_waitcnt lgkmcnt(0)
	v_mfma_f32_32x32x16_bf16 v[0:15], v[36:39], v[160:163], v[0:15]
	ds_read_b128 v[36:39], v224 offset:6144
	s_waitcnt vmcnt(0) lgkmcnt(0)
	v_mfma_f32_32x32x16_bf16 v[16:31], v[36:39], v[152:155], v[16:31]
	ds_read_b128 v[36:39], v224 offset:6656
	s_waitcnt lgkmcnt(0)
	v_mfma_f32_32x32x16_bf16 v[0:15], v[36:39], v[152:155], v[0:15]
	s_nop 15
	s_nop 7
	s_cbranch_vccnz .LBB0_88
	v_lshlrev_b32_e32 v35, 2, v232
	v_or_b32_e32 v36, 32, v35
	v_cmp_le_i32_e32 vcc, v36, v222
	v_or_b32_e32 v36, 33, v35
	s_nop 6
	v_cndmask_b32_e32 v0, v244, v0, vcc
	v_cmp_lt_i32_e32 vcc, v35, v222
	s_nop 1
	v_cndmask_b32_e32 v17, v244, v17, vcc
	v_cmp_le_i32_e32 vcc, v35, v222
	s_nop 1
	v_cndmask_b32_e32 v16, v244, v16, vcc
	v_cmp_le_i32_e32 vcc, v36, v222
	v_or_b32_e32 v36, 2, v35
	s_nop 0
	v_cndmask_b32_e32 v1, v244, v1, vcc
	v_cmp_le_i32_e32 vcc, v36, v222
	v_or_b32_e32 v36, 34, v35
	s_nop 0
	v_cndmask_b32_e32 v18, v244, v18, vcc
	v_cmp_le_i32_e32 vcc, v36, v222
	v_or_b32_e32 v36, 3, v35
	s_nop 0
	v_cndmask_b32_e32 v2, v244, v2, vcc
	v_cmp_le_i32_e32 vcc, v36, v222
	v_or_b32_e32 v36, 35, v35
	s_nop 0
	v_cndmask_b32_e32 v19, v244, v19, vcc
	v_cmp_le_i32_e32 vcc, v36, v222
	v_or_b32_e32 v36, 8, v35
	s_nop 0
	v_cndmask_b32_e32 v3, v244, v3, vcc
	v_cmp_le_i32_e32 vcc, v36, v222
	v_or_b32_e32 v36, 40, v35
	s_nop 0
	v_cndmask_b32_e32 v20, v244, v20, vcc
	v_cmp_le_i32_e32 vcc, v36, v222
	v_or_b32_e32 v36, 9, v35
	s_nop 0
	v_cndmask_b32_e32 v4, v244, v4, vcc
	v_cmp_le_i32_e32 vcc, v36, v222
	v_or_b32_e32 v36, 41, v35
	s_nop 0
	v_cndmask_b32_e32 v21, v244, v21, vcc
	v_cmp_le_i32_e32 vcc, v36, v222
	v_or_b32_e32 v36, 10, v35
	s_nop 0
	v_cndmask_b32_e32 v5, v244, v5, vcc
	v_cmp_le_i32_e32 vcc, v36, v222
	v_or_b32_e32 v36, 42, v35
	s_nop 0
	v_cndmask_b32_e32 v22, v244, v22, vcc
	v_cmp_le_i32_e32 vcc, v36, v222
	v_or_b32_e32 v36, 11, v35
	s_nop 0
	v_cndmask_b32_e32 v6, v244, v6, vcc
	v_cmp_le_i32_e32 vcc, v36, v222
	v_or_b32_e32 v36, 43, v35
	s_nop 0
	v_cndmask_b32_e32 v23, v244, v23, vcc
	v_cmp_le_i32_e32 vcc, v36, v222
	v_or_b32_e32 v36, 16, v35
	s_nop 0
	v_cndmask_b32_e32 v7, v244, v7, vcc
	v_cmp_le_i32_e32 vcc, v36, v222
	v_or_b32_e32 v36, 48, v35
	s_nop 0
	v_cndmask_b32_e32 v24, v244, v24, vcc
	v_cmp_le_i32_e32 vcc, v36, v222
	v_or_b32_e32 v36, 17, v35
	s_nop 0
	v_cndmask_b32_e32 v8, v244, v8, vcc
	v_cmp_le_i32_e32 vcc, v36, v222
	v_or_b32_e32 v36, 49, v35
	s_nop 0
	v_cndmask_b32_e32 v25, v244, v25, vcc
	v_cmp_le_i32_e32 vcc, v36, v222
	v_or_b32_e32 v36, 18, v35
	s_nop 0
	v_cndmask_b32_e32 v9, v244, v9, vcc
	v_cmp_le_i32_e32 vcc, v36, v222
	v_or_b32_e32 v36, 50, v35
	s_nop 0
	v_cndmask_b32_e32 v26, v244, v26, vcc
	v_cmp_le_i32_e32 vcc, v36, v222
	v_or_b32_e32 v36, 19, v35
	s_nop 0
	v_cndmask_b32_e32 v10, v244, v10, vcc
	v_cmp_le_i32_e32 vcc, v36, v222
	v_or_b32_e32 v36, 51, v35
	s_nop 0
	v_cndmask_b32_e32 v27, v244, v27, vcc
	v_cmp_le_i32_e32 vcc, v36, v222
	v_or_b32_e32 v36, 24, v35
	s_nop 0
	v_cndmask_b32_e32 v11, v244, v11, vcc
	v_cmp_le_i32_e32 vcc, v36, v222
	v_or_b32_e32 v36, 56, v35
	s_nop 0
	v_cndmask_b32_e32 v28, v244, v28, vcc
	v_cmp_le_i32_e32 vcc, v36, v222
	v_or_b32_e32 v36, 25, v35
	s_nop 0
	v_cndmask_b32_e32 v12, v244, v12, vcc
	v_cmp_le_i32_e32 vcc, v36, v222
	v_or_b32_e32 v36, 57, v35
	s_nop 0
	v_cndmask_b32_e32 v29, v244, v29, vcc
	v_cmp_le_i32_e32 vcc, v36, v222
	v_or_b32_e32 v36, 26, v35
	s_nop 0
	v_cndmask_b32_e32 v13, v244, v13, vcc
	v_cmp_le_i32_e32 vcc, v36, v222
	v_or_b32_e32 v36, 58, v35
	s_nop 0
	v_cndmask_b32_e32 v30, v244, v30, vcc
	v_cmp_le_i32_e32 vcc, v36, v222
	v_or_b32_e32 v36, 27, v35
	v_or_b32_e32 v35, 59, v35
	v_cndmask_b32_e32 v14, v244, v14, vcc
	v_cmp_le_i32_e32 vcc, v36, v222
	s_nop 1
	v_cndmask_b32_e32 v31, v244, v31, vcc
	v_cmp_le_i32_e32 vcc, v35, v222
	s_nop 1
	v_cndmask_b32_e32 v15, v244, v15, vcc
